# v14: v13 + next-row x prefetch (L2 warm-up loads, counted waits) in both adaLN-norm loops
# baseline (speedup 1.0000x reference)
.LBB0_331:
	s_or_b64 exec, exec, s[12:13]
	v_mov_b32_e32 v18, s14
	v_mov_b32_e32 v19, s34
	v_cndmask_b32_e32 v18, v18, v19, vcc
	v_mov_b32_e32 v19, s3
	v_mov_b32_e32 v20, s37
	v_add_u32_e32 v18, v18, v64
	v_cndmask_b32_e32 v21, v19, v20, vcc
	v_mov_b32_e32 v19, s2
	v_mov_b32_e32 v20, s36
	v_readlane_b32 s12, v255, 25
	v_cndmask_b32_e32 v20, v19, v20, vcc
	v_ashrrev_i32_e32 v19, 31, v18
	v_readlane_b32 s13, v255, 26
	v_lshlrev_b64 v[18:19], 12, v[18:19]
	v_lshl_add_u64 v[18:19], v[20:21], 0, v[18:19]
	v_lshl_add_u64 v[16:17], v[16:17], 2, s[12:13]
	s_mov_b64 s[12:13], 0x1000
	v_lshl_add_u64 v[20:21], v[16:17], 0, s[12:13]
	v_lshl_add_u64 v[22:23], v[20:21], 0, v[112:113]
	v_lshl_add_u64 v[18:19], v[18:19], 0, v[112:113]
	s_mov_b64 s[98:99], 0x800000
	v_lshl_add_u64 v[80:81], v[18:19], 0, s[98:99]
	global_load_dwordx4 v[52:55], v[22:23], off
	v_lshl_add_u64 v[22:23], v[16:17], 0, v[112:113]
	global_load_dwordx4 v[60:63], v[18:19], off nt
	global_load_dwordx4 v[56:59], v[22:23], off
	global_load_dwordx4 v[48:51], v[18:19], off offset:1024 nt
	v_mov_b32_e32 v69, v113
	v_lshl_add_u64 v[16:17], v[20:21], 0, v[68:69]
	v_mov_b32_e32 v71, v113
	global_load_dwordx4 v[40:43], v[16:17], off
	global_load_dwordx4 v[44:47], v[22:23], off offset:1024
	global_load_dwordx4 v[36:39], v[18:19], off offset:2048 nt
	v_lshl_add_u64 v[16:17], v[20:21], 0, v[70:71]
	global_load_dwordx4 v[28:31], v[16:17], off
	global_load_dwordx4 v[32:35], v[22:23], off offset:2048
	s_nop 0
	global_load_dwordx4 v[16:19], v[18:19], off offset:3072 nt
	v_mov_b32_e32 v73, v113
	v_lshl_add_u64 v[20:21], v[20:21], 0, v[72:73]
	global_load_dwordx4 v[24:27], v[20:21], off
	s_nop 0
	global_load_dwordx4 v[20:23], v[22:23], off offset:3072
	v_add_u32_e32 v64, s30, v64
	s_nop 0
	v_readfirstlane_b32 s98, v64
	s_cmpk_lt_i32 s98, 0x4000
	s_cbranch_scc0 .Ln1_nopf
	global_load_dword v82, v[80:81], off
	global_load_dword v82, v[80:81], off offset:1024
	global_load_dword v82, v[80:81], off offset:2048
	global_load_dword v82, v[80:81], off offset:3072
	s_waitcnt vmcnt(4) lgkmcnt(0)
	s_branch .Ln1_pfjoin

.Ln1_pfjoin:
	v_pk_add_f32 v[52:53], v[52:53], 1.0 op_sel_hi:[1,0]
	v_pk_add_f32 v[54:55], v[54:55], 1.0 op_sel_hi:[1,0]
	v_mov_b32_e32 v76, v61
	v_mov_b32_e32 v77, v49
	v_mov_b32_e32 v74, v60
	v_mov_b32_e32 v75, v48
	v_pk_mul_f32 v[76:77], v[76:77], v[76:77]
	v_mov_b32_e32 v78, v37
	v_pk_fma_f32 v[74:75], v[74:75], v[74:75], v[76:77]
	v_mov_b32_e32 v76, v62
	v_mov_b32_e32 v77, v50
	v_pk_fma_f32 v[74:75], v[76:77], v[76:77], v[74:75]
	v_mov_b32_e32 v76, v63
	v_mov_b32_e32 v77, v51
	v_mov_b32_e32 v79, v17
	v_pk_fma_f32 v[74:75], v[76:77], v[76:77], v[74:75]
	v_mov_b32_e32 v76, v36
	v_mov_b32_e32 v77, v16
	v_pk_mul_f32 v[78:79], v[78:79], v[78:79]
	v_add_f32_e32 v65, v74, v75
	v_pk_fma_f32 v[76:77], v[76:77], v[76:77], v[78:79]
	v_mov_b32_e32 v78, v38
	v_mov_b32_e32 v79, v18
	v_pk_fma_f32 v[76:77], v[78:79], v[78:79], v[76:77]
	v_mov_b32_e32 v78, v39
	v_mov_b32_e32 v79, v19
	v_pk_fma_f32 v[76:77], v[78:79], v[78:79], v[76:77]
	v_pk_add_f32 v[40:41], v[40:41], 1.0 op_sel_hi:[1,0]
	v_add_f32_e32 v65, v65, v76
	v_add_f32_e32 v65, v65, v77
	v_pk_add_f32 v[28:29], v[28:29], 1.0 op_sel_hi:[1,0]
	v_pk_add_f32 v[24:25], v[24:25], 1.0 op_sel_hi:[1,0]
	v_add_f32_dpp v65, v65, v65 quad_perm:[1,0,3,2] row_mask:0xf bank_mask:0xf bound_ctrl:1
	v_pk_add_f32 v[42:43], v[42:43], 1.0 op_sel_hi:[1,0]
	v_pk_add_f32 v[30:31], v[30:31], 1.0 op_sel_hi:[1,0]
	v_add_f32_dpp v65, v65, v65 quad_perm:[2,3,0,1] row_mask:0xf bank_mask:0xf bound_ctrl:1
	s_nop 1
	v_add_f32_dpp v65, v65, v65 row_half_mirror row_mask:0xf bank_mask:0xf bound_ctrl:1
	s_nop 1
	v_add_f32_dpp v65, v65, v65 row_mirror row_mask:0xf bank_mask:0xf bound_ctrl:1
	s_nop 0
	v_readlane_b32 s15, v65, 16
	v_readlane_b32 s16, v65, 48
	v_readlane_b32 s12, v65, 0
	v_readlane_b32 s13, v65, 32
	v_mov_b32_e32 v74, s15
	v_mov_b32_e32 v75, s16
	v_pk_add_f32 v[74:75], s[12:13], v[74:75]
	s_movk_i32 s12, 0x43ff
	v_add_f32_e32 v65, v74, v75
	v_fmamk_f32 v65, v65, 0x3a800000, v248
	v_cmp_gt_f32_e32 vcc, s77, v65
	v_mul_f32_e32 v69, 0x4b800000, v65
	s_nop 0
	v_cndmask_b32_e32 v65, v65, v69, vcc
	v_rsq_f32_e32 v65, v65
	s_nop 0
	v_mul_f32_e32 v69, 0x45800000, v65
	v_cndmask_b32_e32 v74, v65, v69, vcc
	v_pk_mul_f32 v[60:61], v[60:61], v[74:75] op_sel_hi:[1,0]
	v_pk_mul_f32 v[48:49], v[48:49], v[74:75] op_sel_hi:[1,0]
	v_pk_mul_f32 v[36:37], v[36:37], v[74:75] op_sel_hi:[1,0]
	v_pk_mul_f32 v[60:61], v[0:1], v[60:61]
	v_pk_mul_f32 v[48:49], v[4:5], v[48:49]
	v_pk_mul_f32 v[36:37], v[8:9], v[36:37]
	v_pk_mul_f32 v[16:17], v[16:17], v[74:75] op_sel_hi:[1,0]
	v_pk_fma_f32 v[52:53], v[52:53], v[60:61], v[56:57]
	v_pk_mul_f32 v[56:57], v[62:63], v[74:75] op_sel_hi:[1,0]
	v_pk_fma_f32 v[40:41], v[40:41], v[48:49], v[44:45]
	v_pk_mul_f32 v[44:45], v[50:51], v[74:75] op_sel_hi:[1,0]
	v_pk_fma_f32 v[28:29], v[28:29], v[36:37], v[32:33]
	v_pk_mul_f32 v[32:33], v[38:39], v[74:75] op_sel_hi:[1,0]
	v_pk_mul_f32 v[16:17], v[12:13], v[16:17]
	v_pk_mul_f32 v[18:19], v[18:19], v[74:75] op_sel_hi:[1,0]
	v_pk_mul_f32 v[56:57], v[2:3], v[56:57]
	v_pk_mul_f32 v[44:45], v[6:7], v[44:45]
	v_pk_mul_f32 v[32:33], v[10:11], v[32:33]
	v_pk_fma_f32 v[16:17], v[24:25], v[16:17], v[20:21]
	v_pk_mul_f32 v[18:19], v[14:15], v[18:19]
	v_pk_add_f32 v[20:21], v[26:27], 1.0 op_sel_hi:[1,0]
	v_pk_fma_f32 v[54:55], v[54:55], v[56:57], v[58:59]
	v_pk_fma_f32 v[42:43], v[42:43], v[44:45], v[46:47]
	v_pk_fma_f32 v[30:31], v[30:31], v[32:33], v[34:35]
	v_pk_fma_f32 v[18:19], v[20:21], v[18:19], v[22:23]
	v_cvt_pk_bf16_f32 v52, v52, v53
	v_cvt_pk_bf16_f32 v53, v54, v55
	v_cvt_pk_bf16_f32 v40, v40, v41
	v_cvt_pk_bf16_f32 v41, v42, v43
	v_cvt_pk_bf16_f32 v28, v28, v29
	v_cvt_pk_bf16_f32 v29, v30, v31
	v_cvt_pk_bf16_f32 v16, v16, v17
	v_cvt_pk_bf16_f32 v17, v18, v19
	v_cmp_lt_i32_e32 vcc, s12, v64
	global_store_dwordx2 v[66:67], v[52:53], off
	global_store_dwordx2 v[66:67], v[40:41], off offset:512
	global_store_dwordx2 v[66:67], v[28:29], off offset:1024
	global_store_dwordx2 v[66:67], v[16:17], off offset:1536
	v_lshl_add_u64 v[66:67], v[66:67], 0, s[18:19]
	s_or_b64 s[10:11], vcc, s[10:11]
	s_andn2_b64 exec, exec, s[10:11]
	s_cbranch_execz .LBB0_334

.LBB0_1621:
	s_or_b64 exec, exec, s[12:13]
	v_mov_b32_e32 v16, 0xffff8000
	v_cndmask_b32_e64 v16, v16, 0, vcc
	v_mov_b32_e32 v17, s3
	v_mov_b32_e32 v18, s7
	v_add_u32_e32 v16, v16, v36
	v_cndmask_b32_e32 v19, v17, v18, vcc
	v_mov_b32_e32 v17, s2
	v_mov_b32_e32 v18, s6
	v_cndmask_b32_e32 v18, v17, v18, vcc
	v_ashrrev_i32_e32 v17, 31, v16
	v_lshlrev_b64 v[16:17], 12, v[16:17]
	v_lshl_add_u64 v[16:17], v[18:19], 0, v[16:17]
	v_lshl_add_u64 v[16:17], v[16:17], 0, v[112:113]
	s_mov_b64 s[98:99], 0x800000
	v_lshl_add_u64 v[118:119], v[16:17], 0, s[98:99]
	global_load_dwordx4 v[28:31], v[16:17], off nt
	global_load_dwordx4 v[24:27], v[16:17], off offset:1024 nt
	global_load_dwordx4 v[20:23], v[16:17], off offset:2048 nt
	s_nop 0
	global_load_dwordx4 v[16:19], v[16:17], off offset:3072 nt
	v_readlane_b32 s12, v255, 25
	v_readlane_b32 s13, v255, 26
	v_mov_b32_e32 v41, v113
	v_mov_b32_e32 v45, v113
	v_lshl_add_u64 v[32:33], v[32:33], 2, s[12:13]
	s_mov_b64 s[12:13], 0x4000
	v_lshl_add_u64 v[114:115], v[32:33], 0, s[12:13]
	v_lshl_add_u64 v[116:117], v[32:33], 0, s[24:25]
	v_lshl_add_u64 v[114:115], v[114:115], 0, v[112:113]
	v_lshl_add_u64 v[116:117], v[116:117], 0, v[112:113]
	global_load_dwordx4 v[80:83], v[114:115], off
	global_load_dwordx4 v[84:87], v[116:117], off
	global_load_dwordx4 v[88:91], v[114:115], off offset:1024
	global_load_dwordx4 v[92:95], v[116:117], off offset:1024
	global_load_dwordx4 v[96:99], v[114:115], off offset:2048
	global_load_dwordx4 v[100:103], v[116:117], off offset:2048
	global_load_dwordx4 v[104:107], v[114:115], off offset:3072
	global_load_dwordx4 v[108:111], v[116:117], off offset:3072
	v_readfirstlane_b32 s98, v36
	s_cmpk_lt_i32 s98, 0x7800
	s_cbranch_scc0 .Lffn_nopf
	global_load_dword v120, v[118:119], off
	global_load_dword v120, v[118:119], off offset:1024
	global_load_dword v120, v[118:119], off offset:2048
	global_load_dword v120, v[118:119], off offset:3072
	s_waitcnt vmcnt(4)
	s_branch .Lffn_pfjoin

.Lffn_pfjoin:
	v_lshl_add_u64 v[48:49], v[32:33], 0, s[12:13]
	v_lshl_add_u64 v[34:35], v[48:49], 0, v[112:113]
	v_lshl_add_u64 v[50:51], v[32:33], 0, s[24:25]
	v_mov_b64_e32 v[52:53], v[80:81]
	v_mov_b64_e32 v[54:55], v[82:83]
	v_lshl_add_u64 v[32:33], v[50:51], 0, v[112:113]
	v_mov_b64_e32 v[32:33], v[84:85]
	v_mov_b64_e32 v[34:35], v[86:87]
	v_add_u32_e32 v36, s30, v36
	s_waitcnt lgkmcnt(0)
	v_mov_b32_e32 v56, v29
	v_mov_b32_e32 v57, v25
	v_mov_b32_e32 v46, v28
	v_mov_b32_e32 v47, v24
	v_pk_mul_f32 v[56:57], v[56:57], v[56:57]
	v_mov_b32_e32 v58, v20
	v_pk_fma_f32 v[46:47], v[46:47], v[46:47], v[56:57]
	v_mov_b32_e32 v56, v21
	v_mov_b32_e32 v57, v17
	v_mov_b32_e32 v59, v16
	v_pk_mul_f32 v[56:57], v[56:57], v[56:57]
	s_waitcnt vmcnt(4)
	v_pk_add_f32 v[60:61], v[54:55], 1.0 op_sel_hi:[1,0]
	v_pk_fma_f32 v[56:57], v[58:59], v[58:59], v[56:57]
	v_mov_b32_e32 v58, v30
	v_mov_b32_e32 v59, v26
	v_pk_fma_f32 v[46:47], v[58:59], v[58:59], v[46:47]
	v_mov_b32_e32 v58, v22
	v_mov_b32_e32 v59, v18
	v_pk_fma_f32 v[56:57], v[58:59], v[58:59], v[56:57]
	v_mov_b32_e32 v58, v31
	v_mov_b32_e32 v59, v27
	v_pk_fma_f32 v[46:47], v[58:59], v[58:59], v[46:47]
	v_mov_b32_e32 v58, v23
	v_mov_b32_e32 v59, v19
	v_pk_fma_f32 v[56:57], v[58:59], v[58:59], v[56:57]
	v_add_f32_e32 v37, v46, v47
	v_add_f32_e32 v37, v37, v56
	v_add_f32_e32 v37, v37, v57
	v_lshl_add_u64 v[56:57], v[48:49], 0, v[40:41]
	v_pk_add_f32 v[58:59], v[52:53], 1.0 op_sel_hi:[1,0]
	v_add_f32_dpp v37, v37, v37 quad_perm:[1,0,3,2] row_mask:0xf bank_mask:0xf bound_ctrl:1
	v_mov_b64_e32 v[52:53], v[88:89]
	v_mov_b64_e32 v[54:55], v[90:91]
	s_nop 0
	v_add_f32_dpp v37, v37, v37 quad_perm:[2,3,0,1] row_mask:0xf bank_mask:0xf bound_ctrl:1
	s_nop 1
	v_add_f32_dpp v37, v37, v37 row_half_mirror row_mask:0xf bank_mask:0xf bound_ctrl:1
	s_nop 1
	v_add_f32_dpp v37, v37, v37 row_mirror row_mask:0xf bank_mask:0xf bound_ctrl:1
	s_nop 0
	v_readlane_b32 s14, v37, 16
	v_readlane_b32 s15, v37, 48
	v_readlane_b32 s12, v37, 0
	v_readlane_b32 s13, v37, 32
	v_mov_b32_e32 v46, s14
	v_mov_b32_e32 v47, s15
	v_pk_add_f32 v[46:47], s[12:13], v[46:47]
	v_readlane_b32 s12, v254, 21
	v_add_f32_e32 v37, v46, v47
	v_fmamk_f32 v37, v37, 0x3a800000, v248
	v_mul_f32_e32 v43, 0x4b800000, v37
	v_cmp_gt_f32_e32 vcc, s77, v37
	v_readlane_b32 s13, v254, 22
	s_nop 0
	v_cndmask_b32_e32 v37, v37, v43, vcc
	v_rsq_f32_e32 v37, v37
	s_nop 0
	v_mul_f32_e32 v43, 0x45800000, v37
	v_cndmask_b32_e32 v46, v37, v43, vcc
	v_pk_mul_f32 v[28:29], v[28:29], v[46:47] op_sel_hi:[1,0]
	v_pk_mul_f32 v[30:31], v[30:31], v[46:47] op_sel_hi:[1,0]
	v_pk_mul_f32 v[28:29], v[0:1], v[28:29]
	v_pk_mul_f32 v[30:31], v[2:3], v[30:31]
	v_pk_fma_f32 v[28:29], v[58:59], v[28:29], v[32:33]
	v_lshl_add_u64 v[32:33], v[50:51], 0, v[40:41]
	v_pk_fma_f32 v[30:31], v[60:61], v[30:31], v[34:35]
	v_mov_b64_e32 v[32:33], v[92:93]
	v_mov_b64_e32 v[34:35], v[94:95]
	v_mov_b32_e32 v43, v113
	v_pk_mul_f32 v[24:25], v[24:25], v[46:47] op_sel_hi:[1,0]
	v_lshl_add_u64 v[56:57], v[48:49], 0, v[42:43]
	v_pk_mul_f32 v[26:27], v[26:27], v[46:47] op_sel_hi:[1,0]
	v_pk_mul_f32 v[24:25], v[4:5], v[24:25]
	v_pk_mul_f32 v[26:27], v[6:7], v[26:27]
	v_lshl_add_u64 v[48:49], v[48:49], 0, v[44:45]
	v_pk_mul_f32 v[16:17], v[16:17], v[46:47] op_sel_hi:[1,0]
	v_pk_mul_f32 v[18:19], v[18:19], v[46:47] op_sel_hi:[1,0]
	v_pk_mul_f32 v[16:17], v[12:13], v[16:17]
	v_pk_mul_f32 v[18:19], v[14:15], v[18:19]
	v_cvt_pk_bf16_f32 v28, v28, v29
	v_cvt_pk_bf16_f32 v29, v30, v31
	v_cmp_le_i32_e32 vcc, s40, v36
	s_or_b64 s[10:11], vcc, s[10:11]
	s_waitcnt vmcnt(4) lgkmcnt(0)
	v_pk_add_f32 v[58:59], v[52:53], 1.0 op_sel_hi:[1,0]
	v_pk_add_f32 v[60:61], v[54:55], 1.0 op_sel_hi:[1,0]
	v_mov_b64_e32 v[52:53], v[96:97]
	v_mov_b64_e32 v[54:55], v[98:99]
	v_pk_mul_f32 v[56:57], v[20:21], v[46:47] op_sel_hi:[1,0]
	v_pk_fma_f32 v[24:25], v[58:59], v[24:25], v[32:33]
	v_lshl_add_u64 v[32:33], v[50:51], 0, v[42:43]
	v_lshl_add_u64 v[50:51], v[50:51], 0, v[44:45]
	v_pk_fma_f32 v[26:27], v[60:61], v[26:27], v[34:35]
	v_mov_b64_e32 v[32:33], v[100:101]
	v_mov_b64_e32 v[34:35], v[102:103]
	v_pk_mul_f32 v[58:59], v[22:23], v[46:47] op_sel_hi:[1,0]
	v_mov_b64_e32 v[20:21], v[104:105]
	v_mov_b64_e32 v[22:23], v[106:107]
	s_nop 0
	v_mov_b64_e32 v[48:49], v[108:109]
	v_mov_b64_e32 v[50:51], v[110:111]
	v_pk_mul_f32 v[56:57], v[8:9], v[56:57]
	v_pk_mul_f32 v[58:59], v[10:11], v[58:59]
	v_cvt_pk_bf16_f32 v24, v24, v25
	v_cvt_pk_bf16_f32 v25, v26, v27
	s_waitcnt vmcnt(4) lgkmcnt(0)
	v_pk_add_f32 v[52:53], v[52:53], 1.0 op_sel_hi:[1,0]
	v_pk_add_f32 v[54:55], v[54:55], 1.0 op_sel_hi:[1,0]
	v_pk_fma_f32 v[32:33], v[52:53], v[56:57], v[32:33]
	v_pk_add_f32 v[20:21], v[20:21], 1.0 op_sel_hi:[1,0]
	v_pk_fma_f32 v[34:35], v[54:55], v[58:59], v[34:35]
	v_pk_fma_f32 v[16:17], v[20:21], v[16:17], v[48:49]
	v_pk_add_f32 v[20:21], v[22:23], 1.0 op_sel_hi:[1,0]
	v_cvt_pk_bf16_f32 v16, v16, v17
	v_pk_fma_f32 v[18:19], v[20:21], v[18:19], v[50:51]
	v_cvt_pk_bf16_f32 v26, v32, v33
	v_cvt_pk_bf16_f32 v17, v18, v19
	v_cvt_pk_bf16_f32 v27, v34, v35
	global_store_dwordx2 v[38:39], v[28:29], off
	global_store_dwordx2 v[38:39], v[24:25], off offset:512
	global_store_dwordx2 v[38:39], v[26:27], off offset:1024
	global_store_dwordx2 v[38:39], v[16:17], off offset:1536
	v_lshl_add_u64 v[38:39], v[38:39], 0, s[12:13]
	s_andn2_b64 exec, exec, s[10:11]
	s_cbranch_execz .LBB0_1624
